# GDN scan: s_setprio 3 for the two compute waves (serial chain + output wave) over the six stager waves during the chunk loop
# speedup vs baseline: 1.0010x; 1.0010x over previous
.LBB0_520:
	s_lshl_b32 s37, s37, 8
	v_lshrrev_b32_e32 v5, 4, v3
	v_lshl_or_b32 v3, v3, 2, s37
	v_or_b32_e32 v24, s34, v3
	v_readlane_b32 s54, v255, 30
	v_ashrrev_i32_e32 v25, 31, v24
	v_readlane_b32 s55, v255, 31
	s_cmp_gt_u32 s12, 63
	v_and_b32_e32 v1, 15, v1
	v_lshl_add_u64 v[24:25], v[24:25], 2, s[54:55]
	global_load_dword v120, v[24:25], off
	s_cselect_b64 s[54:55], -1, 0
	s_lshl_b32 s5, s5, 2
	v_lshlrev_b32_e32 v24, 2, v5
	s_movk_i32 s12, 0x88
	s_add_u32 s5, s30, s5
	v_mad_u32_u24 v3, v1, s12, v24
	s_addc_u32 s12, s31, 0
	s_lshl_b32 s4, s4, 2
	s_add_u32 s4, s5, s4
	s_addc_u32 s5, s12, 0
	v_lshlrev_b32_e32 v16, 2, v1
	v_lshl_add_u64 v[92:93], s[4:5], 0, v[16:17]
	s_sub_i32 s4, s13, 54
	s_cmp_lt_u32 s4, 9
	s_cselect_b32 s4, 15, 16
	v_writelane_b32 v255, s4, 35
	s_lshl_b32 s2, s2, 10
	v_writelane_b32 v255, s2, 37
	s_sub_i32 s2, s13, 48
	s_cmp_lt_u32 s2, 9
	s_cselect_b32 s2, 15, 16
	v_writelane_b32 v255, s2, 39
	s_lshl_b32 s2, s60, 10
	v_writelane_b32 v255, s2, 41
	s_sub_i32 s2, s13, 42
	s_cmp_lt_u32 s2, 9
	s_cselect_b32 s2, 15, 16
	v_writelane_b32 v255, s2, 43
	s_lshl_b32 s2, s61, 10
	v_writelane_b32 v255, s2, 45
	s_sub_i32 s2, s13, 36
	s_cmp_lt_u32 s2, 9
	s_cselect_b32 s2, 15, 16
	v_writelane_b32 v255, s2, 47
	s_lshl_b32 s2, s79, 10
	v_writelane_b32 v255, s2, 49
	s_sub_i32 s2, s13, 30
	s_cmp_lt_u32 s2, 9
	s_cselect_b32 s89, 15, 16
	s_lshl_b32 s12, s82, 10
	s_sub_i32 s2, s13, 24
	s_cmp_lt_u32 s2, 9
	s_cselect_b32 s34, 15, 16
	s_lshl_b32 s79, s83, 10
	s_sub_i32 s2, s13, 18
	s_cmp_lt_u32 s2, 9
	s_cselect_b32 s2, 15, 16
	s_lshl_b32 s37, s84, 10
	s_add_i32 s4, s13, -12
	s_cmp_lt_u32 s4, 9
	s_cselect_b32 s82, 15, 16
	s_lshl_b32 s83, s85, 10
	s_add_i32 s4, s13, -6
	s_cmp_lt_u32 s4, 9
	v_lshlrev_b32_e32 v7, 6, v1
	s_cselect_b32 s84, 15, 16
	s_lshl_b32 s4, s86, 10
	v_lshlrev_b32_e32 v123, 1, v3
	v_sub_u32_e32 v3, v3, v7
	s_cmp_lt_u32 s13, 9
	v_mov_b32_e32 v19, v17
	v_lshlrev_b32_e32 v121, 3, v5
	v_mul_u32_u24_e32 v122, 0x110, v1
	v_lshlrev_b32_e32 v124, 1, v1
	v_lshlrev_b32_e32 v125, 1, v3
	v_mul_u32_u24_e32 v126, 0x90, v1
	v_lshlrev_b32_e32 v127, 7, v5
	v_mov_b32_e32 v3, v17
	v_mov_b32_e32 v1, v17
	v_mov_b32_e32 v7, v17
	v_mov_b32_e32 v5, v17
	v_mov_b32_e32 v11, v17
	v_mov_b32_e32 v9, v17
	v_mov_b32_e32 v15, v17
	v_mov_b32_e32 v13, v17
	v_mov_b32_e32 v21, v17
	v_lshl_add_u64 v[112:113], s[44:45], 0, v[18:19]
	s_cselect_b32 s5, 15, 16
	s_lshl_b32 s85, s87, 10
	v_mov_b32_e32 v23, v17
	v_mov_b32_e32 v16, v17
	v_mov_b32_e32 v18, v17
	v_lshl_add_u64 v[94:95], s[44:45], 0, v[2:3]
	v_lshl_add_u64 v[96:97], s[44:45], 0, v[0:1]
	v_lshl_add_u64 v[98:99], s[44:45], 0, v[6:7]
	v_lshl_add_u64 v[100:101], s[44:45], 0, v[4:5]
	v_lshl_add_u64 v[102:103], s[44:45], 0, v[10:11]
	v_lshl_add_u64 v[104:105], s[44:45], 0, v[8:9]
	v_lshl_add_u64 v[106:107], s[44:45], 0, v[14:15]
	v_lshl_add_u64 v[108:109], s[44:45], 0, v[12:13]
	v_lshl_add_u64 v[110:111], s[44:45], 0, v[20:21]
	s_cmp_eq_u32 s13, 2
	v_lshl_add_u64 v[114:115], s[44:45], 0, v[22:23]
	v_add_u32_e32 v116, s35, v24
	v_mov_b64_e32 v[0:1], v[16:17]
	v_mov_b64_e32 v[4:5], v[16:17]
	v_mov_b64_e32 v[8:9], v[16:17]
	v_mov_b64_e32 v[12:13], v[16:17]
	v_mov_b64_e32 v[22:23], v[18:19]
	v_mov_b64_e32 v[26:27], v[18:19]
	v_mov_b64_e32 v[30:31], v[18:19]
	s_waitcnt lgkmcnt(0)
	v_mov_b64_e32 v[34:35], v[18:19]
	s_cselect_b32 s13, 15, 16
	s_lshl_b32 s86, s88, 10
	s_mov_b32 s35, 0
	v_mov_b64_e32 v[2:3], v[18:19]
	v_mov_b64_e32 v[6:7], v[18:19]
	v_mov_b64_e32 v[10:11], v[18:19]
	v_mov_b64_e32 v[14:15], v[18:19]
	v_mov_b64_e32 v[20:21], v[16:17]
	v_mov_b64_e32 v[24:25], v[16:17]
	v_mov_b64_e32 v[28:29], v[16:17]
	v_mov_b64_e32 v[32:33], v[16:17]
	s_mov_b32 s87, 0
	v_readfirstlane_b32 s98, v228
	s_lshr_b32 s98, s98, 7
	s_cmp_eq_u32 s98, 0
	s_cbranch_scc0 .Lscan_prio_skip
	s_setprio 3
.Lscan_prio_skip:
	s_waitcnt vmcnt(0)
	s_barrier
	s_branch .LBB0_523

.LBB0_566:
	s_setprio 0
	s_waitcnt vmcnt(0)
	v_mov_b32_e32 v0, v228
	s_barrier
	s_nop 0
	v_cmp_eq_u32_e32 vcc, 0, v0
	s_and_saveexec_b64 s[8:9], vcc
	v_readlane_b32 s19, v255, 27
	s_cbranch_execz .LBB0_568
	v_readlane_b32 s4, v255, 18
	v_readlane_b32 s5, v255, 19
	s_and_b32 s2, s4, 7
	s_lshl_b32 s2, s2, 4
	s_lshr_b32 s4, s4, 3
	s_or_b32 s4, s4, s2
	s_ashr_i32 s4, s4, 3
	s_ashr_i32 s5, s4, 31
	s_lshl_b64 s[4:5], s[4:5], 2
	s_add_u32 s4, s19, s4
	v_readlane_b32 s2, v255, 26
	s_addc_u32 s5, s2, s5
	buffer_wbl2 sc1
	s_waitcnt vmcnt(0)
	v_mov_b64_e32 v[0:1], s[4:5]
	global_atomic_add v[0:1], v230, off
